# QK-norm epilogue: cross-row sums via permlane16/32 swaps instead of LDS permutes
# speedup vs baseline: 1.0246x; 1.0032x over previous
;     __device__ __forceinline__ void operator()(const f32x4 (&acc)[2][2][4][2], const Unit& u, int wr, int wc, int fr, int fq) const {
;     ...
;                 if (gn) { float ss = 0.f;
; #pragma unroll
;                     for (int bj = 0; bj < 2; ++bj)
; #pragma unroll
;                         for (int n = 0; n < 2; ++n) { const f32x4 v = acc[ai][bj][m][n]; ss += (v.x * v.x + v.y * v.y) + (v.z * v.z + v.w * v.w); }
;                     ss += __shfl_xor(ss, 16); ss += __shfl_xor(ss, 32);
;                     rs = __builtin_amdgcn_rsqf(ss * (1.f / 64.f) + EPS); }
.LBB0_166:
	s_and_b64 vcc, exec, s[10:11]
	s_cbranch_vccnz .LBB0_168
	v_pk_mul_f32 v[164:165], v[118:119], v[118:119]
	v_pk_mul_f32 v[166:167], v[116:117], v[116:117]
	v_mul_f32_e32 v152, v120, v120
	v_pk_mov_b32 v[168:169], v[166:167], v[164:165] op_sel:[1,0]
	v_mov_b32_e32 v167, v165
	v_pk_add_f32 v[164:165], v[168:169], v[166:167]
	v_pk_mul_f32 v[166:167], v[114:115], v[114:115]
	v_pk_mul_f32 v[168:169], v[112:113], v[112:113]
	v_pk_add_f32 v[164:165], v[164:165], v[164:165] op_sel:[0,1] op_sel_hi:[1,0]
	v_pk_mov_b32 v[170:171], v[168:169], v[166:167] op_sel:[1,0]
	v_mov_b32_e32 v169, v167
	v_pk_add_f32 v[166:167], v[170:171], v[168:169]
	v_mul_f32_e32 v168, v121, v121
	v_pk_add_f32 v[166:167], v[166:167], v[166:167] op_sel:[0,1] op_sel_hi:[1,0]
	v_mov_b32_e32 v165, v152
	v_mov_b32_e32 v167, v168
	v_mul_f32_e32 v152, v125, v125
	v_mul_f32_e32 v169, v122, v122
	v_pk_add_f32 v[164:165], v[164:165], v[166:167]
	v_pk_fma_f32 v[166:167], v[124:125], v[124:125], v[152:153] op_sel_hi:[1,1,0]
	v_mul_f32_e32 v152, v127, v127
	v_mul_f32_e32 v170, v123, v123
	v_mov_b32_e32 v167, v169
	v_pk_fma_f32 v[168:169], v[126:127], v[126:127], v[152:153] op_sel_hi:[1,1,0]
	s_nop 0
	v_mov_b32_e32 v169, v170
	v_pk_add_f32 v[166:167], v[166:167], v[168:169]
	s_nop 0
	v_pk_add_f32 v[164:165], v[164:165], v[166:167]
	s_nop 0
	v_add_f32_e32 v152, v164, v165
	v_mov_b32_e32 v164, v152
	s_nop 1
	v_permlane16_swap_b32_e32 v152, v164
	v_add_f32_e32 v152, v152, v164
	v_mov_b32_e32 v164, v152
	s_nop 1
	v_permlane32_swap_b32_e32 v152, v164
	v_add_f32_e32 v152, v152, v164
	v_fmamk_f32 v152, v152, 0x3c800000, v187
	v_rsq_f32_e32 v172, v152
	s_branch .LBB0_169

;     __device__ __forceinline__ void operator()(const f32x4 (&acc)[2][2][4][2], const Unit& u, int wr, int wc, int fr, int fq) const {
;     ...
;                 if (gn) { float ss = 0.f;
; #pragma unroll
;                     for (int bj = 0; bj < 2; ++bj)
; #pragma unroll
;                         for (int n = 0; n < 2; ++n) { const f32x4 v = acc[ai][bj][m][n]; ss += (v.x * v.x + v.y * v.y) + (v.z * v.z + v.w * v.w); }
;                     ss += __shfl_xor(ss, 16); ss += __shfl_xor(ss, 32);
;                     rs = __builtin_amdgcn_rsqf(ss * (1.f / 64.f) + EPS); }
.LBB0_180:
	v_pk_mul_f32 v[112:113], v[102:103], v[102:103]
	v_pk_mul_f32 v[114:115], v[100:101], v[100:101]
	s_nop 0
	v_pk_mov_b32 v[116:117], v[114:115], v[112:113] op_sel:[1,0]
	v_mov_b32_e32 v115, v113
	v_pk_add_f32 v[112:113], v[116:117], v[114:115]
	v_pk_mul_f32 v[114:115], v[98:99], v[98:99]
	v_pk_mul_f32 v[116:117], v[96:97], v[96:97]
	v_pk_add_f32 v[112:113], v[112:113], v[112:113] op_sel:[0,1] op_sel_hi:[1,0]
	v_pk_mov_b32 v[118:119], v[116:117], v[114:115] op_sel:[1,0]
	v_mov_b32_e32 v117, v115
	v_pk_add_f32 v[114:115], v[118:119], v[116:117]
	v_mul_f32_e32 v116, v104, v104
	v_mul_f32_e32 v117, v105, v105
	v_pk_add_f32 v[114:115], v[114:115], v[114:115] op_sel:[0,1] op_sel_hi:[1,0]
	v_mov_b32_e32 v113, v116
	v_mov_b32_e32 v115, v117
	v_pk_add_f32 v[112:113], v[112:113], v[114:115]
	v_mul_f32_e32 v114, v109, v109
	v_mul_f32_e32 v116, v111, v111
	v_mul_f32_e32 v118, v106, v106
	v_mul_f32_e32 v119, v107, v107
	v_pk_fma_f32 v[114:115], v[108:109], v[108:109], v[114:115] op_sel_hi:[1,1,0]
	v_pk_fma_f32 v[116:117], v[110:111], v[110:111], v[116:117] op_sel_hi:[1,1,0]
	v_mov_b32_e32 v115, v118
	v_mov_b32_e32 v117, v119
	v_pk_add_f32 v[114:115], v[114:115], v[116:117]
	s_nop 0
	v_pk_add_f32 v[112:113], v[112:113], v[114:115]
	v_add_f32_e32 v112, v112, v113
	v_mov_b32_e32 v113, v112
	s_nop 1
	v_permlane16_swap_b32_e32 v112, v113
	v_add_f32_e32 v112, v112, v113
	v_mov_b32_e32 v113, v112
	s_nop 1
	v_permlane32_swap_b32_e32 v112, v113
	v_add_f32_e32 v112, v112, v113
	v_fmamk_f32 v112, v112, 0x3c800000, v187
	v_rsq_f32_e32 v118, v112
	s_branch .LBB0_186

;     __device__ __forceinline__ void operator()(const f32x4 (&acc)[2][2][4][2], const Unit& u, int wr, int wc, int fr, int fq) const {
;     ...
;                 if (gn) { float ss = 0.f;
; #pragma unroll
;                     for (int bj = 0; bj < 2; ++bj)
; #pragma unroll
;                         for (int n = 0; n < 2; ++n) { const f32x4 v = acc[ai][bj][m][n]; ss += (v.x * v.x + v.y * v.y) + (v.z * v.z + v.w * v.w); }
;                     ss += __shfl_xor(ss, 16); ss += __shfl_xor(ss, 32);
;                     rs = __builtin_amdgcn_rsqf(ss * (1.f / 64.f) + EPS); }
.LBB0_197:
	v_pk_mul_f32 v[96:97], v[86:87], v[86:87]
	v_pk_mul_f32 v[98:99], v[84:85], v[84:85]
	s_nop 0
	v_pk_mov_b32 v[100:101], v[98:99], v[96:97] op_sel:[1,0]
	v_mov_b32_e32 v99, v97
	v_pk_add_f32 v[96:97], v[100:101], v[98:99]
	v_pk_mul_f32 v[98:99], v[82:83], v[82:83]
	v_pk_mul_f32 v[100:101], v[80:81], v[80:81]
	v_pk_add_f32 v[96:97], v[96:97], v[96:97] op_sel:[0,1] op_sel_hi:[1,0]
	v_pk_mov_b32 v[102:103], v[100:101], v[98:99] op_sel:[1,0]
	v_mov_b32_e32 v101, v99
	v_pk_add_f32 v[98:99], v[102:103], v[100:101]
	v_mul_f32_e32 v100, v88, v88
	v_mul_f32_e32 v101, v89, v89
	v_pk_add_f32 v[98:99], v[98:99], v[98:99] op_sel:[0,1] op_sel_hi:[1,0]
	v_mov_b32_e32 v97, v100
	v_mov_b32_e32 v99, v101
	v_pk_add_f32 v[96:97], v[96:97], v[98:99]
	v_mul_f32_e32 v98, v93, v93
	v_mul_f32_e32 v100, v95, v95
	v_mul_f32_e32 v102, v90, v90
	v_mul_f32_e32 v103, v91, v91
	v_pk_fma_f32 v[98:99], v[92:93], v[92:93], v[98:99] op_sel_hi:[1,1,0]
	v_pk_fma_f32 v[100:101], v[94:95], v[94:95], v[100:101] op_sel_hi:[1,1,0]
	v_mov_b32_e32 v99, v102
	v_mov_b32_e32 v101, v103
	v_pk_add_f32 v[98:99], v[98:99], v[100:101]
	s_nop 0
	v_pk_add_f32 v[96:97], v[96:97], v[98:99]
	v_add_f32_e32 v96, v96, v97
	v_mov_b32_e32 v97, v96
	s_nop 1
	v_permlane16_swap_b32_e32 v96, v97
	v_add_f32_e32 v96, v96, v97
	v_mov_b32_e32 v97, v96
	s_nop 1
	v_permlane32_swap_b32_e32 v96, v97
	v_add_f32_e32 v96, v96, v97
	v_fmamk_f32 v96, v96, 0x3c800000, v187
	v_rsq_f32_e32 v102, v96
	s_branch .LBB0_203

;     __device__ __forceinline__ void operator()(const f32x4 (&acc)[2][2][4][2], const Unit& u, int wr, int wc, int fr, int fq) const {
;     ...
;                 if (gn) { float ss = 0.f;
; #pragma unroll
;                     for (int bj = 0; bj < 2; ++bj)
; #pragma unroll
;                         for (int n = 0; n < 2; ++n) { const f32x4 v = acc[ai][bj][m][n]; ss += (v.x * v.x + v.y * v.y) + (v.z * v.z + v.w * v.w); }
;                     ss += __shfl_xor(ss, 16); ss += __shfl_xor(ss, 32);
;                     rs = __builtin_amdgcn_rsqf(ss * (1.f / 64.f) + EPS); }
.LBB0_214:
	v_pk_mul_f32 v[80:81], v[70:71], v[70:71]
	v_pk_mul_f32 v[82:83], v[68:69], v[68:69]
	s_nop 0
	v_pk_mov_b32 v[84:85], v[82:83], v[80:81] op_sel:[1,0]
	v_mov_b32_e32 v83, v81
	v_pk_add_f32 v[80:81], v[84:85], v[82:83]
	v_pk_mul_f32 v[82:83], v[66:67], v[66:67]
	v_pk_mul_f32 v[84:85], v[64:65], v[64:65]
	v_pk_add_f32 v[80:81], v[80:81], v[80:81] op_sel:[0,1] op_sel_hi:[1,0]
	v_pk_mov_b32 v[86:87], v[84:85], v[82:83] op_sel:[1,0]
	v_mov_b32_e32 v85, v83
	v_pk_add_f32 v[82:83], v[86:87], v[84:85]
	v_mul_f32_e32 v84, v72, v72
	v_mul_f32_e32 v85, v73, v73
	v_pk_add_f32 v[82:83], v[82:83], v[82:83] op_sel:[0,1] op_sel_hi:[1,0]
	v_mov_b32_e32 v81, v84
	v_mov_b32_e32 v83, v85
	v_pk_add_f32 v[80:81], v[80:81], v[82:83]
	v_mul_f32_e32 v82, v77, v77
	v_mul_f32_e32 v84, v79, v79
	v_mul_f32_e32 v86, v74, v74
	v_mul_f32_e32 v87, v75, v75
	v_pk_fma_f32 v[82:83], v[76:77], v[76:77], v[82:83] op_sel_hi:[1,1,0]
	v_pk_fma_f32 v[84:85], v[78:79], v[78:79], v[84:85] op_sel_hi:[1,1,0]
	v_mov_b32_e32 v83, v86
	v_mov_b32_e32 v85, v87
	v_pk_add_f32 v[82:83], v[82:83], v[84:85]
	s_nop 0
	v_pk_add_f32 v[80:81], v[80:81], v[82:83]
	v_add_f32_e32 v80, v80, v81
	v_mov_b32_e32 v81, v80
	s_nop 1
	v_permlane16_swap_b32_e32 v80, v81
	v_add_f32_e32 v80, v80, v81
	v_mov_b32_e32 v81, v80
	s_nop 1
	v_permlane32_swap_b32_e32 v80, v81
	v_add_f32_e32 v80, v80, v81
	v_fmamk_f32 v80, v80, 0x3c800000, v187
	v_rsq_f32_e32 v86, v80
	s_branch .LBB0_220

;     __device__ __forceinline__ void operator()(const f32x4 (&acc)[2][2][4][2], const Unit& u, int wr, int wc, int fr, int fq) const {
;     ...
;                 if (gn) { float ss = 0.f;
; #pragma unroll
;                     for (int bj = 0; bj < 2; ++bj)
; #pragma unroll
;                         for (int n = 0; n < 2; ++n) { const f32x4 v = acc[ai][bj][m][n]; ss += (v.x * v.x + v.y * v.y) + (v.z * v.z + v.w * v.w); }
;                     ss += __shfl_xor(ss, 16); ss += __shfl_xor(ss, 32);
;                     rs = __builtin_amdgcn_rsqf(ss * (1.f / 64.f) + EPS); }
.LBB0_231:
	v_pk_mul_f32 v[64:65], v[54:55], v[54:55]
	v_pk_mul_f32 v[66:67], v[52:53], v[52:53]
	s_nop 0
	v_pk_mov_b32 v[68:69], v[66:67], v[64:65] op_sel:[1,0]
	v_mov_b32_e32 v67, v65
	v_pk_add_f32 v[64:65], v[68:69], v[66:67]
	v_pk_mul_f32 v[66:67], v[50:51], v[50:51]
	v_pk_mul_f32 v[68:69], v[48:49], v[48:49]
	v_pk_add_f32 v[64:65], v[64:65], v[64:65] op_sel:[0,1] op_sel_hi:[1,0]
	v_pk_mov_b32 v[70:71], v[68:69], v[66:67] op_sel:[1,0]
	v_mov_b32_e32 v69, v67
	v_pk_add_f32 v[66:67], v[70:71], v[68:69]
	v_mul_f32_e32 v68, v56, v56
	v_mul_f32_e32 v69, v57, v57
	v_pk_add_f32 v[66:67], v[66:67], v[66:67] op_sel:[0,1] op_sel_hi:[1,0]
	v_mov_b32_e32 v65, v68
	v_mov_b32_e32 v67, v69
	v_pk_add_f32 v[64:65], v[64:65], v[66:67]
	v_mul_f32_e32 v66, v61, v61
	v_mul_f32_e32 v68, v63, v63
	v_mul_f32_e32 v70, v58, v58
	v_mul_f32_e32 v71, v59, v59
	v_pk_fma_f32 v[66:67], v[60:61], v[60:61], v[66:67] op_sel_hi:[1,1,0]
	v_pk_fma_f32 v[68:69], v[62:63], v[62:63], v[68:69] op_sel_hi:[1,1,0]
	v_mov_b32_e32 v67, v70
	v_mov_b32_e32 v69, v71
	v_pk_add_f32 v[66:67], v[66:67], v[68:69]
	s_nop 0
	v_pk_add_f32 v[64:65], v[64:65], v[66:67]
	v_add_f32_e32 v64, v64, v65
	v_mov_b32_e32 v65, v64
	s_nop 1
	v_permlane16_swap_b32_e32 v64, v65
	v_add_f32_e32 v64, v64, v65
	v_mov_b32_e32 v65, v64
	s_nop 1
	v_permlane32_swap_b32_e32 v64, v65
	v_add_f32_e32 v64, v64, v65
	v_fmamk_f32 v64, v64, 0x3c800000, v187
	v_rsq_f32_e32 v70, v64
	s_branch .LBB0_237

;     __device__ __forceinline__ void operator()(const f32x4 (&acc)[2][2][4][2], const Unit& u, int wr, int wc, int fr, int fq) const {
;     ...
;                 if (gn) { float ss = 0.f;
; #pragma unroll
;                     for (int bj = 0; bj < 2; ++bj)
; #pragma unroll
;                         for (int n = 0; n < 2; ++n) { const f32x4 v = acc[ai][bj][m][n]; ss += (v.x * v.x + v.y * v.y) + (v.z * v.z + v.w * v.w); }
;                     ss += __shfl_xor(ss, 16); ss += __shfl_xor(ss, 32);
;                     rs = __builtin_amdgcn_rsqf(ss * (1.f / 64.f) + EPS); }
.LBB0_248:
	v_pk_mul_f32 v[48:49], v[38:39], v[38:39]
	v_pk_mul_f32 v[50:51], v[36:37], v[36:37]
	s_nop 0
	v_pk_mov_b32 v[52:53], v[50:51], v[48:49] op_sel:[1,0]
	v_mov_b32_e32 v51, v49
	v_pk_add_f32 v[48:49], v[52:53], v[50:51]
	v_pk_mul_f32 v[50:51], v[34:35], v[34:35]
	v_pk_mul_f32 v[52:53], v[32:33], v[32:33]
	v_pk_add_f32 v[48:49], v[48:49], v[48:49] op_sel:[0,1] op_sel_hi:[1,0]
	v_pk_mov_b32 v[54:55], v[52:53], v[50:51] op_sel:[1,0]
	v_mov_b32_e32 v53, v51
	v_pk_add_f32 v[50:51], v[54:55], v[52:53]
	v_mul_f32_e32 v52, v40, v40
	v_mul_f32_e32 v53, v41, v41
	v_pk_add_f32 v[50:51], v[50:51], v[50:51] op_sel:[0,1] op_sel_hi:[1,0]
	v_mov_b32_e32 v49, v52
	v_mov_b32_e32 v51, v53
	v_pk_add_f32 v[48:49], v[48:49], v[50:51]
	v_mul_f32_e32 v50, v45, v45
	v_mul_f32_e32 v52, v47, v47
	v_mul_f32_e32 v54, v42, v42
	v_mul_f32_e32 v55, v43, v43
	v_pk_fma_f32 v[50:51], v[44:45], v[44:45], v[50:51] op_sel_hi:[1,1,0]
	v_pk_fma_f32 v[52:53], v[46:47], v[46:47], v[52:53] op_sel_hi:[1,1,0]
	v_mov_b32_e32 v51, v54
	v_mov_b32_e32 v53, v55
	v_pk_add_f32 v[50:51], v[50:51], v[52:53]
	s_nop 0
	v_pk_add_f32 v[48:49], v[48:49], v[50:51]
	v_add_f32_e32 v48, v48, v49
	v_mov_b32_e32 v49, v48
	s_nop 1
	v_permlane16_swap_b32_e32 v48, v49
	v_add_f32_e32 v48, v48, v49
	v_mov_b32_e32 v49, v48
	s_nop 1
	v_permlane32_swap_b32_e32 v48, v49
	v_add_f32_e32 v48, v48, v49
	v_fmamk_f32 v48, v48, 0x3c800000, v187
	v_rsq_f32_e32 v54, v48
	s_branch .LBB0_254

;     __device__ __forceinline__ void operator()(const f32x4 (&acc)[2][2][4][2], const Unit& u, int wr, int wc, int fr, int fq) const {
;     ...
;                 if (gn) { float ss = 0.f;
; #pragma unroll
;                     for (int bj = 0; bj < 2; ++bj)
; #pragma unroll
;                         for (int n = 0; n < 2; ++n) { const f32x4 v = acc[ai][bj][m][n]; ss += (v.x * v.x + v.y * v.y) + (v.z * v.z + v.w * v.w); }
;                     ss += __shfl_xor(ss, 16); ss += __shfl_xor(ss, 32);
;                     rs = __builtin_amdgcn_rsqf(ss * (1.f / 64.f) + EPS); }
.LBB0_265:
	v_pk_mul_f32 v[32:33], v[22:23], v[22:23]
	v_pk_mul_f32 v[34:35], v[20:21], v[20:21]
	s_nop 0
	v_pk_mov_b32 v[36:37], v[34:35], v[32:33] op_sel:[1,0]
	v_mov_b32_e32 v35, v33
	v_pk_add_f32 v[32:33], v[36:37], v[34:35]
	v_pk_mul_f32 v[34:35], v[18:19], v[18:19]
	v_pk_mul_f32 v[36:37], v[16:17], v[16:17]
	v_pk_add_f32 v[32:33], v[32:33], v[32:33] op_sel:[0,1] op_sel_hi:[1,0]
	v_pk_mov_b32 v[38:39], v[36:37], v[34:35] op_sel:[1,0]
	v_mov_b32_e32 v37, v35
	v_pk_add_f32 v[34:35], v[38:39], v[36:37]
	v_mul_f32_e32 v36, v24, v24
	v_mul_f32_e32 v37, v25, v25
	v_pk_add_f32 v[34:35], v[34:35], v[34:35] op_sel:[0,1] op_sel_hi:[1,0]
	v_mov_b32_e32 v33, v36
	v_mov_b32_e32 v35, v37
	v_pk_add_f32 v[32:33], v[32:33], v[34:35]
	v_mul_f32_e32 v34, v29, v29
	v_mul_f32_e32 v36, v31, v31
	v_mul_f32_e32 v38, v26, v26
	v_mul_f32_e32 v39, v27, v27
	v_pk_fma_f32 v[34:35], v[28:29], v[28:29], v[34:35] op_sel_hi:[1,1,0]
	v_pk_fma_f32 v[36:37], v[30:31], v[30:31], v[36:37] op_sel_hi:[1,1,0]
	v_mov_b32_e32 v35, v38
	v_mov_b32_e32 v37, v39
	v_pk_add_f32 v[34:35], v[34:35], v[36:37]
	s_nop 0
	v_pk_add_f32 v[32:33], v[32:33], v[34:35]
	v_add_f32_e32 v32, v32, v33
	v_mov_b32_e32 v33, v32
	s_nop 1
	v_permlane16_swap_b32_e32 v32, v33
	v_add_f32_e32 v32, v32, v33
	v_mov_b32_e32 v33, v32
	s_nop 1
	v_permlane32_swap_b32_e32 v32, v33
	v_add_f32_e32 v32, v32, v33
	v_fmamk_f32 v32, v32, 0x3c800000, v187
	v_rsq_f32_e32 v38, v32
	s_branch .LBB0_271

;     __device__ __forceinline__ void operator()(const f32x4 (&acc)[2][2][4][2], const Unit& u, int wr, int wc, int fr, int fq) const {
;     ...
;                 if (gn) { float ss = 0.f;
; #pragma unroll
;                     for (int bj = 0; bj < 2; ++bj)
; #pragma unroll
;                         for (int n = 0; n < 2; ++n) { const f32x4 v = acc[ai][bj][m][n]; ss += (v.x * v.x + v.y * v.y) + (v.z * v.z + v.w * v.w); }
;                     ss += __shfl_xor(ss, 16); ss += __shfl_xor(ss, 32);
;                     rs = __builtin_amdgcn_rsqf(ss * (1.f / 64.f) + EPS); }
.LBB0_282:
	v_pk_mul_f32 v[16:17], v[6:7], v[6:7]
	v_pk_mul_f32 v[18:19], v[4:5], v[4:5]
	s_nop 0
	v_pk_mov_b32 v[20:21], v[18:19], v[16:17] op_sel:[1,0]
	v_mov_b32_e32 v19, v17
	v_pk_add_f32 v[16:17], v[20:21], v[18:19]
	v_pk_mul_f32 v[18:19], v[2:3], v[2:3]
	v_pk_mul_f32 v[20:21], v[0:1], v[0:1]
	v_pk_add_f32 v[16:17], v[16:17], v[16:17] op_sel:[0,1] op_sel_hi:[1,0]
	v_pk_mov_b32 v[22:23], v[20:21], v[18:19] op_sel:[1,0]
	v_mov_b32_e32 v21, v19
	v_pk_add_f32 v[18:19], v[22:23], v[20:21]
	v_mul_f32_e32 v20, v8, v8
	v_mul_f32_e32 v21, v9, v9
	v_pk_add_f32 v[18:19], v[18:19], v[18:19] op_sel:[0,1] op_sel_hi:[1,0]
	v_mov_b32_e32 v17, v20
	v_mov_b32_e32 v19, v21
	v_pk_add_f32 v[16:17], v[16:17], v[18:19]
	v_mul_f32_e32 v18, v13, v13
	v_mul_f32_e32 v20, v15, v15
	v_mul_f32_e32 v22, v10, v10
	v_mul_f32_e32 v23, v11, v11
	v_pk_fma_f32 v[18:19], v[12:13], v[12:13], v[18:19] op_sel_hi:[1,1,0]
	v_pk_fma_f32 v[20:21], v[14:15], v[14:15], v[20:21] op_sel_hi:[1,1,0]
	v_mov_b32_e32 v19, v22
	v_mov_b32_e32 v21, v23
	v_pk_add_f32 v[18:19], v[18:19], v[20:21]
	s_nop 0
	v_pk_add_f32 v[16:17], v[16:17], v[18:19]
	v_add_f32_e32 v16, v16, v17
	v_mov_b32_e32 v17, v16
	s_nop 1
	v_permlane16_swap_b32_e32 v16, v17
	v_add_f32_e32 v16, v16, v17
	v_mov_b32_e32 v17, v16
	s_nop 1
	v_permlane32_swap_b32_e32 v16, v17
	v_add_f32_e32 v16, v16, v17
	v_fmamk_f32 v16, v16, 0x3c800000, v187
	v_rsq_f32_e32 v22, v16
	s_branch .LBB0_288
